# v75 + phase 0 latent position-DFT table: per-workgroup 1024-entry cos/sin bf16 table in LDS (2 entries per thread, same sincospif sequence), elements become one ds_read + two 2-byte stores
# baseline (speedup 1.0000x reference)
.LBB0_1881:
	s_or_b64 exec, exec, s[4:5]
	s_mov_b32 s17, 0x7060302
	v_and_b32_e32 v9, 0x3ff, v202
	v_mov_b32_e32 v10, v9
	v_cvt_f32_u32_e32 v10, v10
	v_mul_f32_e32 v10, 0x3b000000, v10
	v_mul_f32_e32 v11, 0.5, v10
	v_fract_f32_e32 v12, v11
	v_add_f32_e32 v12, v12, v12
	v_cmp_neq_f32_e32 vcc, s30, v11
	s_nop 1
	v_cndmask_b32_e32 v11, 0, v12, vcc
	v_cmp_lt_f32_e32 vcc, 1.0, v10
	s_nop 1
	v_cndmask_b32_e32 v11, v10, v11, vcc
	v_add_f32_e32 v12, v11, v11
	v_rndne_f32_e32 v12, v12
	v_fmac_f32_e32 v11, -0.5, v12
	v_cvt_i32_f32_e32 v12, v12
	v_mul_f32_e32 v13, v11, v11
	v_fmamk_f32 v14, v13, 0x3e75aa41, v199
	v_fmamk_f32 v16, v13, 0x3d4be544, v200
	v_fmaak_f32 v14, v13, v14, 0x40234736
	v_fmaak_f32 v16, v13, v16, 0xbfaad1da
	v_mul_f32_e32 v15, v11, v13
	v_fmaak_f32 v14, v13, v14, 0xc0a55e0e
	v_fmaak_f32 v16, v13, v16, 0x4081e0d3
	v_lshlrev_b32_e32 v17, 30, v12
	v_and_b32_e32 v12, 1, v12
	v_mul_f32_e32 v14, v15, v14
	v_fmaak_f32 v15, v13, v16, 0xc09de9e6
	v_fmac_f32_e32 v14, 0x40490fdb, v11
	v_fma_f32 v11, v13, v15, 1.0
	v_cmp_eq_u32_e32 vcc, 0, v12
	v_xor_b32_e32 v13, 0x80000000, v14
	s_nop 0
	v_cndmask_b32_e32 v12, v11, v14, vcc
	v_bitop3_b32 v12, v12, v17, s33 bitop3:0x78
	v_cndmask_b32_e32 v11, v13, v11, vcc
	v_mul_f32_e32 v12, 0x3d000000, v12
	v_cmp_lg_f32_e32 vcc, s30, v10
	v_bitop3_b32 v10, v11, v17, s33 bitop3:0x78
	v_mul_f32_e32 v10, 0x3d000000, v10
	v_cndmask_b32_e32 v11, v212, v12, vcc
	v_cndmask_b32_e32 v10, v212, v10, vcc
	v_bfe_u32 v12, v11, 16, 1
	v_bfe_u32 v13, v10, 16, 1
	v_add3_u32 v11, v11, v12, s37
	v_add3_u32 v10, v10, v13, s37
	v_perm_b32 v10, v11, v10, s17
	v_lshlrev_b32_e32 v9, 2, v9
	v_add_u32_e32 v9, 0x22000, v9
	ds_write_b32 v9, v10
	v_and_b32_e32 v9, 0x3ff, v202
	v_add_u32_e32 v9, 0x200, v9
	v_mov_b32_e32 v10, v9
	v_cvt_f32_u32_e32 v10, v10
	v_mul_f32_e32 v10, 0x3b000000, v10
	v_mul_f32_e32 v11, 0.5, v10
	v_fract_f32_e32 v12, v11
	v_add_f32_e32 v12, v12, v12
	v_cmp_neq_f32_e32 vcc, s30, v11
	s_nop 1
	v_cndmask_b32_e32 v11, 0, v12, vcc
	v_cmp_lt_f32_e32 vcc, 1.0, v10
	s_nop 1
	v_cndmask_b32_e32 v11, v10, v11, vcc
	v_add_f32_e32 v12, v11, v11
	v_rndne_f32_e32 v12, v12
	v_fmac_f32_e32 v11, -0.5, v12
	v_cvt_i32_f32_e32 v12, v12
	v_mul_f32_e32 v13, v11, v11
	v_fmamk_f32 v14, v13, 0x3e75aa41, v199
	v_fmamk_f32 v16, v13, 0x3d4be544, v200
	v_fmaak_f32 v14, v13, v14, 0x40234736
	v_fmaak_f32 v16, v13, v16, 0xbfaad1da
	v_mul_f32_e32 v15, v11, v13
	v_fmaak_f32 v14, v13, v14, 0xc0a55e0e
	v_fmaak_f32 v16, v13, v16, 0x4081e0d3
	v_lshlrev_b32_e32 v17, 30, v12
	v_and_b32_e32 v12, 1, v12
	v_mul_f32_e32 v14, v15, v14
	v_fmaak_f32 v15, v13, v16, 0xc09de9e6
	v_fmac_f32_e32 v14, 0x40490fdb, v11
	v_fma_f32 v11, v13, v15, 1.0
	v_cmp_eq_u32_e32 vcc, 0, v12
	v_xor_b32_e32 v13, 0x80000000, v14
	s_nop 0
	v_cndmask_b32_e32 v12, v11, v14, vcc
	v_bitop3_b32 v12, v12, v17, s33 bitop3:0x78
	v_cndmask_b32_e32 v11, v13, v11, vcc
	v_mul_f32_e32 v12, 0x3d000000, v12
	v_cmp_lg_f32_e32 vcc, s30, v10
	v_bitop3_b32 v10, v11, v17, s33 bitop3:0x78
	v_mul_f32_e32 v10, 0x3d000000, v10
	v_cndmask_b32_e32 v11, v212, v12, vcc
	v_cndmask_b32_e32 v10, v212, v10, vcc
	v_bfe_u32 v12, v11, 16, 1
	v_bfe_u32 v13, v10, 16, 1
	v_add3_u32 v11, v11, v12, s37
	v_add3_u32 v10, v10, v13, s37
	v_perm_b32 v10, v11, v10, s17
	v_lshlrev_b32_e32 v9, 2, v9
	v_add_u32_e32 v9, 0x22000, v9
	ds_write_b32 v9, v10
	s_waitcnt lgkmcnt(0)
	s_barrier
	s_mov_b32 s4, 0x100000
	v_cmp_gt_i32_e32 vcc, s4, v4
	s_and_saveexec_b64 s[4:5], vcc
	s_cbranch_execz .LBB0_1884
	v_lshl_add_u64 v[6:7], v[4:5], 1, s[10:11]
	s_mov_b64 s[6:7], 0xa00000
	s_ashr_i32 s17, s16, 31
	v_lshl_add_u64 v[6:7], v[6:7], 0, s[6:7]
	s_lshl_b64 s[6:7], s[16:17], 1
	s_mov_b64 s[26:27], 0
	v_mov_b32_e32 v2, v4
.LBB0_1883:
	v_lshrrev_b32_e32 v9, 10, v2
	v_mul_lo_u32 v10, v9, v2
	v_and_b32_e32 v10, 0x3ff, v10
	s_mov_b32 s17, 0xffe00000
	v_add_co_u32_e32 v8, vcc, s17, v6
	v_lshlrev_b32_e32 v10, 2, v10
	v_add_u32_e32 v2, s16, v2
	v_addc_co_u32_e32 v9, vcc, -1, v7, vcc
	v_add_u32_e32 v10, 0x22000, v10
	s_mov_b32 s17, 0xfffff
	ds_read_b32 v10, v10
	v_cmp_lt_i32_e32 vcc, s17, v2
	s_or_b64 s[26:27], vcc, s[26:27]
	s_waitcnt lgkmcnt(0)
	global_store_short_d16_hi v[6:7], v10, off
	v_lshl_add_u64 v[6:7], v[6:7], 0, s[6:7]
	global_store_short v[8:9], v10, off
	s_andn2_b64 exec, exec, s[26:27]
	s_cbranch_execnz .LBB0_1883
